# P3 pass-C items re-dealt: none on the 32 decode out-proj workgroups
# speedup vs baseline: 1.0154x; 1.0024x over previous
.LBB0_635:
	s_or_b64 exec, exec, s[4:5]
	v_readlane_b32 s4, v238, 33
	v_readlane_b32 s5, v238, 34
	v_readlane_b32 s50, v238, 17
	s_andn2_b64 vcc, exec, s[4:5]
	v_readlane_b32 s51, v238, 18
	v_readlane_b32 s96, v238, 29
	s_barrier
	s_cbranch_vccnz .LBB0_662
	v_readlane_b32 s101, v239, 2
	s_mov_b32 s100, 0x200
	s_cmp_lg_u32 s101, 0x100
	s_cbranch_scc1 .Lpc_done
	s_cmpk_ge_i32 s68, 0xc0
	s_cbranch_scc1 .LBB0_662
	s_cmpk_lt_i32 s68, 0x80
	s_cbranch_scc1 .Lpc_a
	s_add_i32 s68, s68, 0x100
	s_mov_b32 s16, 64
	s_branch .Lpc_done
.Lpc_a:
	s_movk_i32 s16, 0x80
	s_mov_b32 s100, 0x180
